# rowsq prefetch: next unit row statistics loaded one unit ahead in gate-up and W_in GEMM epilogues
# baseline (speedup 1.0000x reference)
; #define PG8_GAS __attribute__((address_space(1)))
; #define PG8_STAGE(bufoff, gbase, voff) do { _Pragma("unroll") for (int _i = 0; _i < 2; ++_i) \
;         __builtin_amdgcn_global_load_lds((const unsigned*)((const char*)(gbase) + (voff)[_i]), (PG8_LAS unsigned*)(lds + (bufoff) + ldsw + _i * 8192), 16, 0, 0); } while (0)
; #define PG8_WAIT_V(n) asm volatile("s_waitcnt vmcnt(" #n ")" ::: "memory")
; #define PG8_BAR __builtin_amdgcn_s_barrier()
;     __device__ __forceinline__ void operator()(const f32x4 (&acc)[2][2][4][2], const Unit& u, int wr, int wc, int fr, int fq) const {
;         const int row0 = u.pm * BM + wr * 64 + fr, col0 = u.pn * HALF + wc * 32 + 8 * fq;
;         unsigned long long rq[2][4];
; #pragma unroll
;         for (int ai = 0; ai < 2; ++ai)
; #pragma unroll
;             for (int m = 0; m < 4; ++m) rq[ai][m] = ((const PG8_GAS unsigned long long*)rowsq)[row0 + ai * HALF + m * 16];
; template <class Epi, class Sched, bool ALIGN_EPI = false, bool SP2 = false>
; __device__ __forceinline__ void gemm_phase(PG8_LAS unsigned char* lds, const Gemm g, const Sched& S, const Epi& E, const int tid) {
;     ...
;         PG8_STAGE(PG8_SB(0, 0), cB, voffB); PG8_STAGE(PG8_SA(0, 0), cA, voffA); PG8_STAGE(PG8_SB(0, 1), cB + hstep, voffB); PG8_STAGE(PG8_SA(0, 1), cA + hstep, voffA);
;         if (wr == 1) PG8_BAR;
;         PG8_WAIT_V(4); PG8_BAR;
;         PG8_STAGE(PG8_SB(1, 0), cB + kstep, voffB); PG8_STAGE(PG8_SA(1, 0), cA + kstep, voffA); PG8_STAGE(PG8_SB(1, 1), cB + hstep + kstep, voffB);
;         PG8_WAIT_V(6); PG8_BAR;
.LBB0_205:
	s_lshl_b32 s42, s63, 16
	s_add_u32 s30, s40, 0x2cd00000
	s_addc_u32 s31, s41, 0
	s_add_u32 s40, s40, s42
	s_addc_u32 s41, s41, 0
	s_add_u32 s42, s40, 0x10000
	s_addc_u32 s43, s41, 0
	s_lshl_b32 s40, s46, 5
	s_and_b32 s46, s40, 0x60
	s_add_i32 m0, s61, 0x18000
	v_lshl_add_u64 v[6:7], v[6:7], 0, s[28:29]
	s_lshl_b32 s47, s45, 13
	s_lshl_b32 s48, s46, 7
	s_waitcnt vmcnt(2)
	s_barrier
	global_load_lds_dwordx4 v[6:7], off
	v_lshl_add_u64 v[4:5], v[4:5], 0, s[28:29]
	s_add_i32 m0, s61, 0x1a000
	s_add_i32 s67, s61, 0x8000
	s_add_i32 s68, s61, 0xa000
	global_load_lds_dwordx4 v[4:5], off
	v_lshl_add_u64 v[0:1], v[0:1], 0, s[28:29]
	s_mov_b32 m0, s67
	s_add_u32 s40, s54, 0x80080
	global_load_lds_dwordx4 v[0:1], off
	v_lshl_add_u64 v[0:1], v[2:3], 0, s[28:29]
	s_mov_b32 m0, s68
	s_addc_u32 s41, s55, 0
	global_load_lds_dwordx4 v[0:1], off
	s_add_i32 m0, s61, 0x1c000
	v_lshl_add_u64 v[0:1], s[40:41], 0, v[96:97]
	global_load_lds_dwordx4 v[0:1], off
	v_lshl_add_u64 v[0:1], s[40:41], 0, v[98:99]
	s_add_i32 m0, s61, 0x1e000
	s_cmpk_lt_u32 s44, 0x100
	global_load_lds_dwordx4 v[0:1], off
	v_lshrrev_b32_e32 v1, 1, v8
	v_and_b32_e32 v1, 24, v1
	v_and_b32_e32 v0, 15, v8
	v_lshlrev_b32_e32 v2, 1, v1
	v_lshl_or_b32 v101, s45, 6, v0
	v_lshl_or_b32 v0, v0, 6, v2
	v_lshlrev_b32_e32 v2, 2, v8
	v_and_b32_e32 v2, 32, v2
	v_bitop3_b32 v3, v0, s47, v2 bitop3:0xde
	v_bitop3_b32 v160, s48, v0, v2 bitop3:0xf6
	v_lshlrev_b32_e32 v0, 15, v9
	v_and_b32_e32 v0, 0xffff0000, v0
	v_or_b32_e32 v161, s46, v1
	v_lshl_add_u32 v0, v10, 12, v0
	v_and_b32_e32 v1, 1, v9
	v_lshl_or_b32 v0, v1, 6, v0
	v_lshl_add_u32 v138, v11, 1, v0
	v_lshlrev_b32_e32 v0, 15, v13
	v_and_b32_e32 v0, 0xffff0000, v0
	s_waitcnt vmcnt(6)
	v_lshl_add_u32 v0, v12, 12, v0
	v_and_b32_e32 v1, 1, v13
	v_lshl_or_b32 v0, v1, 6, v0
	v_readlane_b32 s40, v254, 5
	s_cselect_b64 s[44:45], -1, 0
	v_mov_b32_e32 v139, v97
	v_lshl_add_u32 v140, v14, 1, v0
	v_mov_b32_e32 v141, v97
	s_mov_b32 s69, 0
	v_add_u32_e32 v162, 0, v3
	v_readlane_b32 s70, v253, 54
	s_mov_b32 s71, s40
	v_lshl_add_u32 v233, s71, 8, v101
	v_lshlrev_b32_e32 v233, 3, v233
	global_load_dwordx2 v[234:235], v233, s[42:43]
	global_load_dwordx2 v[236:237], v233, s[42:43] offset:128
	global_load_dwordx2 v[238:239], v233, s[42:43] offset:256
	global_load_dwordx2 v[240:241], v233, s[42:43] offset:384
	global_load_dwordx2 v[242:243], v233, s[42:43] offset:1024
	global_load_dwordx2 v[246:247], v233, s[42:43] offset:1152
	global_load_dwordx2 v[248:249], v233, s[42:43] offset:1280
	global_load_dwordx2 v[250:251], v233, s[42:43] offset:1408
	s_barrier
	v_readlane_b32 s41, v254, 6
	s_branch .LBB0_208

; #define PG8_GAS __attribute__((address_space(1)))
; __device__ __forceinline__ float e_silu(float x) { return x * __builtin_amdgcn_rcpf(1.f + e_exp(-x)); }
; __device__ __forceinline__ unsigned e_pk2(float lo, float hi) { typedef float f2 __attribute__((ext_vector_type(2))); typedef __bf16 b2 __attribute__((ext_vector_type(2))); f2 v = {lo, hi}; b2 b = __builtin_convertvector(v, b2); return __builtin_bit_cast(unsigned, b); }
;     __device__ __forceinline__ void operator()(const f32x4 (&acc)[2][2][4][2], const Unit& u, int wr, int wc, int fr, int fq) const {
;         const int row0 = u.pm * BM + wr * 64 + fr, col0 = u.pn * HALF + wc * 32 + 8 * fq;
;         unsigned long long rq[2][4];
; #pragma unroll
;         for (int ai = 0; ai < 2; ++ai)
; #pragma unroll
;             for (int m = 0; m < 4; ++m) rq[ai][m] = ((const PG8_GAS unsigned long long*)rowsq)[row0 + ai * HALF + m * 16];
; #pragma unroll
;         for (int ai = 0; ai < 2; ++ai)
; #pragma unroll
;             for (int m = 0; m < 4; ++m) {
;                 const int row = row0 + ai * HALF + m * 16;
;                 const float rs = __builtin_amdgcn_rsqf((float)rq[ai][m] * (1.0f / (2048.0f * 16777216.0f)) + 1e-6f);
;                 float o[8];
; #pragma unroll
;                 for (int n = 0; n < 2; ++n)
; #pragma unroll
;                     for (int j = 0; j < 4; ++j) { const float g = acc[ai][0][m][n][j] * rs, up = acc[ai][1][m][n][j] * rs; o[4 * n + j] = e_silu(g) * up; }
;                 u32x4 w; w.x = e_pk2(o[0], o[1]); w.y = e_pk2(o[2], o[3]); w.z = e_pk2(o[4], o[5]); w.w = e_pk2(o[6], o[7]);
.LBB0_214:
	v_lshl_add_u32 v156, s71, 8, v101
	v_ashrrev_i32_e32 v157, 31, v156
	v_mov_b64_e32 v[170:171], v[234:235]
	v_mov_b64_e32 v[154:155], v[236:237]
	v_mov_b64_e32 v[152:153], v[238:239]
	v_mov_b64_e32 v[150:151], v[240:241]
	v_mov_b64_e32 v[148:149], v[242:243]
	v_mov_b64_e32 v[146:147], v[246:247]
	v_mov_b64_e32 v[144:145], v[248:249]
	v_mov_b64_e32 v[142:143], v[250:251]
	s_and_b32 s100, s48, 31
	v_lshl_add_u32 v233, s100, 8, v101
	v_lshlrev_b32_e32 v233, 3, v233
	global_load_dwordx2 v[234:235], v233, s[42:43]
	global_load_dwordx2 v[236:237], v233, s[42:43] offset:128
	global_load_dwordx2 v[238:239], v233, s[42:43] offset:256
	global_load_dwordx2 v[240:241], v233, s[42:43] offset:384
	global_load_dwordx2 v[242:243], v233, s[42:43] offset:1024
	global_load_dwordx2 v[246:247], v233, s[42:43] offset:1152
	global_load_dwordx2 v[248:249], v233, s[42:43] offset:1280
	global_load_dwordx2 v[250:251], v233, s[42:43] offset:1408
	v_lshl_or_b32 v158, s70, 7, v161
	v_ashrrev_i32_e32 v159, 31, v158
	v_or_b32_e32 v168, 16, v156
	v_or_b32_e32 v167, 32, v156
	v_or_b32_e32 v166, 48, v156
	v_add_u32_e32 v165, 0x80, v156
	v_add_u32_e32 v164, 0x90, v156
	v_add_u32_e32 v163, 0xa0, v156
	v_add_u32_e32 v157, 0xb0, v156
	s_andn2_b64 vcc, exec, s[40:41]
	s_mov_b32 s80, 0x4b800000
	s_movk_i32 s78, 0x1fff
	v_ffbh_u32_e32 v169, v171
	v_min_u32_e32 v169, 32, v169
	v_lshlrev_b64 v[170:171], v169, v[170:171]
	v_min_u32_e32 v170, 1, v170
	v_or_b32_e32 v170, v171, v170
	v_cvt_f32_u32_e32 v170, v170
	v_sub_u32_e32 v169, 32, v169
	v_ldexp_f32 v169, v170, v169
	v_fmamk_f32 v169, v169, 0x2e000000, v226
	v_rsq_f32_e32 v170, v169
	s_nop 0
	v_pk_mul_f32 v[130:131], v[130:131], v[170:171] op_sel_hi:[1,0]
	s_nop 0
	v_mul_f32_e32 v169, 0xbfb8aa3b, v130
	v_exp_f32_e32 v169, v169
	v_pk_mul_f32 v[122:123], v[122:123], v[170:171] op_sel_hi:[1,0]
	v_pk_mul_f32 v[124:125], v[124:125], v[170:171] op_sel_hi:[1,0]
	v_pk_mul_f32 v[126:127], v[126:127], v[170:171] op_sel_hi:[1,0]
	v_add_f32_e32 v169, 1.0, v169
	v_rcp_f32_e32 v172, v169
	v_mul_f32_e32 v169, 0xbfb8aa3b, v131
	v_exp_f32_e32 v169, v169
	v_pk_mul_f32 v[118:119], v[118:119], v[170:171] op_sel_hi:[1,0]
	v_pk_mul_f32 v[120:121], v[120:121], v[170:171] op_sel_hi:[1,0]
	v_add_f32_e32 v169, 1.0, v169
	v_rcp_f32_e32 v173, v169
	s_nop 0
	v_pk_mul_f32 v[130:131], v[130:131], v[172:173]
	s_nop 0
	v_pk_mul_f32 v[122:123], v[122:123], v[130:131]
	v_pk_mul_f32 v[130:131], v[132:133], v[170:171] op_sel_hi:[1,0]
	s_nop 0
	v_mul_f32_e32 v132, 0xbfb8aa3b, v130
	v_mul_f32_e32 v133, 0xbfb8aa3b, v131
	v_exp_f32_e32 v132, v132
	v_exp_f32_e32 v133, v133
	v_add_f32_e32 v132, 1.0, v132
	v_add_f32_e32 v133, 1.0, v133
	v_rcp_f32_e32 v132, v132
	v_rcp_f32_e32 v133, v133
	s_nop 0
	v_pk_mul_f32 v[130:131], v[130:131], v[132:133]
	s_nop 0
	v_pk_mul_f32 v[124:125], v[124:125], v[130:131]
	v_mul_f32_e32 v130, 0xbfb8aa3b, v126
	v_mul_f32_e32 v131, 0xbfb8aa3b, v127
	v_exp_f32_e32 v130, v130
	v_exp_f32_e32 v131, v131
	v_add_f32_e32 v130, 1.0, v130
	v_add_f32_e32 v131, 1.0, v131
	v_rcp_f32_e32 v130, v130
	v_rcp_f32_e32 v131, v131
	s_nop 0
	v_pk_mul_f32 v[126:127], v[126:127], v[130:131]
	s_nop 0
	v_pk_mul_f32 v[126:127], v[118:119], v[126:127]
	v_pk_mul_f32 v[118:119], v[128:129], v[170:171] op_sel_hi:[1,0]
	s_nop 0
	v_mul_f32_e32 v128, 0xbfb8aa3b, v118
	v_mul_f32_e32 v129, 0xbfb8aa3b, v119
	v_exp_f32_e32 v128, v128
	v_exp_f32_e32 v129, v129
	v_add_f32_e32 v128, 1.0, v128
	v_add_f32_e32 v129, 1.0, v129
	v_rcp_f32_e32 v128, v128
	v_rcp_f32_e32 v129, v129
	s_nop 0
	v_pk_mul_f32 v[118:119], v[118:119], v[128:129]
	s_nop 0
	v_pk_mul_f32 v[128:129], v[120:121], v[118:119]
	v_cvt_pk_bf16_f32 v118, v122, v123
	v_mov_b64_e32 v[122:123], s[30:31]
	v_cvt_pk_bf16_f32 v119, v124, v125
	v_cvt_pk_bf16_f32 v120, v126, v127
	v_mad_i64_i32 v[126:127], s[54:55], v156, s92, v[122:123]
	v_lshlrev_b64 v[124:125], 1, v[158:159]
	v_cvt_pk_bf16_f32 v121, v128, v129
	v_lshl_add_u64 v[126:127], v[126:127], 0, v[124:125]
	global_store_dwordx4 v[126:127], v[118:121], off
	s_nop 1
	v_ffbh_u32_e32 v118, v155
	v_min_u32_e32 v120, 32, v118
	v_lshlrev_b64 v[118:119], v120, v[154:155]
	v_min_u32_e32 v118, 1, v118
	v_or_b32_e32 v118, v119, v118
	v_cvt_f32_u32_e32 v118, v118
	v_sub_u32_e32 v119, 32, v120
	v_ldexp_f32 v118, v118, v119
	v_fmamk_f32 v118, v118, 0x2e000000, v226
	v_rsq_f32_e32 v118, v118
	s_nop 0
	v_pk_mul_f32 v[114:115], v[114:115], v[118:119] op_sel_hi:[1,0]
	s_nop 0
	v_mul_f32_e32 v119, 0xbfb8aa3b, v114
	v_exp_f32_e32 v119, v119
	s_nop 0
	v_add_f32_e32 v119, 1.0, v119
	v_rcp_f32_e32 v120, v119
	v_pk_mul_f32 v[110:111], v[110:111], v[118:119] op_sel_hi:[1,0]
	v_mul_f32_e32 v119, 0xbfb8aa3b, v115
	v_exp_f32_e32 v119, v119
	s_nop 0
	v_add_f32_e32 v119, 1.0, v119
	v_rcp_f32_e32 v121, v119
	v_pk_mul_f32 v[112:113], v[112:113], v[118:119] op_sel_hi:[1,0]
	v_pk_mul_f32 v[106:107], v[106:107], v[118:119] op_sel_hi:[1,0]
	v_pk_mul_f32 v[102:103], v[102:103], v[118:119] op_sel_hi:[1,0]
	v_pk_mul_f32 v[114:115], v[114:115], v[120:121]
	v_pk_mul_f32 v[104:105], v[104:105], v[118:119] op_sel_hi:[1,0]
	v_pk_mul_f32 v[110:111], v[110:111], v[114:115]
	v_pk_mul_f32 v[114:115], v[116:117], v[118:119] op_sel_hi:[1,0]
	s_nop 0
	v_mul_f32_e32 v116, 0xbfb8aa3b, v114
	v_mul_f32_e32 v117, 0xbfb8aa3b, v115
	v_exp_f32_e32 v116, v116
	v_exp_f32_e32 v117, v117
	v_add_f32_e32 v116, 1.0, v116
	v_add_f32_e32 v117, 1.0, v117
	v_rcp_f32_e32 v116, v116
	v_rcp_f32_e32 v117, v117
	s_nop 0
	v_pk_mul_f32 v[114:115], v[114:115], v[116:117]
	s_nop 0
	v_pk_mul_f32 v[112:113], v[112:113], v[114:115]
	v_mul_f32_e32 v114, 0xbfb8aa3b, v106
	v_mul_f32_e32 v115, 0xbfb8aa3b, v107
	v_exp_f32_e32 v114, v114
; #define PG8_GAS __attribute__((address_space(1)))
; __device__ __forceinline__ float e_silu(float x) { return x * __builtin_amdgcn_rcpf(1.f + e_exp(-x)); }
; __device__ __forceinline__ unsigned e_pk2(float lo, float hi) { typedef float f2 __attribute__((ext_vector_type(2))); typedef __bf16 b2 __attribute__((ext_vector_type(2))); f2 v = {lo, hi}; b2 b = __builtin_convertvector(v, b2); return __builtin_bit_cast(unsigned, b); }
;     __device__ __forceinline__ void operator()(const f32x4 (&acc)[2][2][4][2], const Unit& u, int wr, int wc, int fr, int fq) const {
;     ...
;                 const int row = row0 + ai * HALF + m * 16;
;                 const float rs = __builtin_amdgcn_rsqf((float)rq[ai][m] * (1.0f / (2048.0f * 16777216.0f)) + 1e-6f);
;                 float o[8];
; #pragma unroll
;                 for (int n = 0; n < 2; ++n)
; #pragma unroll
;                     for (int j = 0; j < 4; ++j) { const float g = acc[ai][0][m][n][j] * rs, up = acc[ai][1][m][n][j] * rs; o[4 * n + j] = e_silu(g) * up; }
;                 u32x4 w; w.x = e_pk2(o[0], o[1]); w.y = e_pk2(o[2], o[3]); w.z = e_pk2(o[4], o[5]); w.w = e_pk2(o[6], o[7]);
;                 *(PG8_GAS u32x4*)(ACT + (size_t)row * ldc + col0) = w;
	v_exp_f32_e32 v115, v115
	v_add_f32_e32 v114, 1.0, v114
	v_add_f32_e32 v115, 1.0, v115
	v_rcp_f32_e32 v114, v114
	v_rcp_f32_e32 v115, v115
	s_nop 0
	v_pk_mul_f32 v[106:107], v[106:107], v[114:115]
	s_nop 0
	v_pk_mul_f32 v[106:107], v[102:103], v[106:107]
	v_pk_mul_f32 v[102:103], v[108:109], v[118:119] op_sel_hi:[1,0]
	s_nop 0
	v_mul_f32_e32 v108, 0xbfb8aa3b, v102
	v_mul_f32_e32 v109, 0xbfb8aa3b, v103
	v_exp_f32_e32 v108, v108
	v_exp_f32_e32 v109, v109
	v_add_f32_e32 v108, 1.0, v108
	v_add_f32_e32 v109, 1.0, v109
	v_rcp_f32_e32 v108, v108
	v_rcp_f32_e32 v109, v109
	s_nop 0
	v_pk_mul_f32 v[102:103], v[102:103], v[108:109]
	s_nop 0
	v_pk_mul_f32 v[108:109], v[104:105], v[102:103]
	v_cvt_pk_bf16_f32 v104, v106, v107
	v_mad_i64_i32 v[106:107], s[54:55], v168, s92, v[122:123]
	v_cvt_pk_bf16_f32 v102, v110, v111
	v_cvt_pk_bf16_f32 v103, v112, v113
	v_cvt_pk_bf16_f32 v105, v108, v109
	v_lshl_add_u64 v[106:107], v[106:107], 0, v[124:125]
	global_store_dwordx4 v[106:107], v[102:105], off
	s_nop 1
	v_ffbh_u32_e32 v102, v153
	v_min_u32_e32 v104, 32, v102
	v_lshlrev_b64 v[102:103], v104, v[152:153]
	v_min_u32_e32 v102, 1, v102
	v_or_b32_e32 v102, v103, v102
	v_cvt_f32_u32_e32 v102, v102
	v_sub_u32_e32 v103, 32, v104
	v_ldexp_f32 v102, v102, v103
	v_fmamk_f32 v102, v102, 0x2e000000, v226
	v_rsq_f32_e32 v102, v102
	s_nop 0
	v_pk_mul_f32 v[92:93], v[92:93], v[102:103] op_sel_hi:[1,0]
	s_nop 0
	v_mul_f32_e32 v103, 0xbfb8aa3b, v92
	v_exp_f32_e32 v103, v103
	s_nop 0
	v_add_f32_e32 v103, 1.0, v103
	v_rcp_f32_e32 v104, v103
	v_pk_mul_f32 v[88:89], v[88:89], v[102:103] op_sel_hi:[1,0]
	v_mul_f32_e32 v103, 0xbfb8aa3b, v93
	v_exp_f32_e32 v103, v103
	s_nop 0
	v_add_f32_e32 v103, 1.0, v103
	v_rcp_f32_e32 v105, v103
	v_pk_mul_f32 v[90:91], v[90:91], v[102:103] op_sel_hi:[1,0]
	v_pk_mul_f32 v[84:85], v[84:85], v[102:103] op_sel_hi:[1,0]
	v_pk_mul_f32 v[80:81], v[80:81], v[102:103] op_sel_hi:[1,0]
	v_pk_mul_f32 v[92:93], v[92:93], v[104:105]
	v_pk_mul_f32 v[82:83], v[82:83], v[102:103] op_sel_hi:[1,0]
	v_pk_mul_f32 v[88:89], v[88:89], v[92:93]
	v_pk_mul_f32 v[92:93], v[94:95], v[102:103] op_sel_hi:[1,0]
	s_nop 0
	v_mul_f32_e32 v94, 0xbfb8aa3b, v92
	v_mul_f32_e32 v95, 0xbfb8aa3b, v93
	v_exp_f32_e32 v94, v94
	v_exp_f32_e32 v95, v95
	v_add_f32_e32 v94, 1.0, v94
	v_add_f32_e32 v95, 1.0, v95
	v_rcp_f32_e32 v94, v94
	v_rcp_f32_e32 v95, v95
	s_nop 0
	v_pk_mul_f32 v[92:93], v[92:93], v[94:95]
	s_nop 0
	v_pk_mul_f32 v[90:91], v[90:91], v[92:93]
	v_mul_f32_e32 v92, 0xbfb8aa3b, v84
	v_mul_f32_e32 v93, 0xbfb8aa3b, v85
	v_exp_f32_e32 v92, v92
	v_exp_f32_e32 v93, v93
	v_add_f32_e32 v92, 1.0, v92
	v_add_f32_e32 v93, 1.0, v93
	v_rcp_f32_e32 v92, v92
	v_rcp_f32_e32 v93, v93
	s_nop 0
	v_pk_mul_f32 v[84:85], v[84:85], v[92:93]
	s_nop 0
	v_pk_mul_f32 v[84:85], v[80:81], v[84:85]
	v_pk_mul_f32 v[80:81], v[86:87], v[102:103] op_sel_hi:[1,0]
	s_nop 0
	v_mul_f32_e32 v86, 0xbfb8aa3b, v80
	v_mul_f32_e32 v87, 0xbfb8aa3b, v81
	v_exp_f32_e32 v86, v86
	v_exp_f32_e32 v87, v87
	v_add_f32_e32 v86, 1.0, v86
	v_add_f32_e32 v87, 1.0, v87
	v_rcp_f32_e32 v86, v86
	v_rcp_f32_e32 v87, v87
	s_nop 0
	v_pk_mul_f32 v[80:81], v[80:81], v[86:87]
	s_nop 0
	v_pk_mul_f32 v[86:87], v[82:83], v[80:81]
	v_cvt_pk_bf16_f32 v82, v84, v85
	v_mad_i64_i32 v[84:85], s[54:55], v167, s92, v[122:123]
	v_cvt_pk_bf16_f32 v80, v88, v89
	v_cvt_pk_bf16_f32 v81, v90, v91
	v_cvt_pk_bf16_f32 v83, v86, v87
	v_lshl_add_u64 v[84:85], v[84:85], 0, v[124:125]
	global_store_dwordx4 v[84:85], v[80:83], off
	s_nop 1
	v_ffbh_u32_e32 v80, v151
	v_min_u32_e32 v82, 32, v80
	v_lshlrev_b64 v[80:81], v82, v[150:151]
	v_min_u32_e32 v80, 1, v80
	v_or_b32_e32 v80, v81, v80
	v_cvt_f32_u32_e32 v80, v80
	v_sub_u32_e32 v81, 32, v82
	v_ldexp_f32 v80, v80, v81
	v_fmamk_f32 v80, v80, 0x2e000000, v226
	v_rsq_f32_e32 v80, v80
	s_nop 0
	v_pk_mul_f32 v[76:77], v[76:77], v[80:81] op_sel_hi:[1,0]
	s_nop 0
	v_mul_f32_e32 v81, 0xbfb8aa3b, v76
	v_exp_f32_e32 v81, v81
	s_nop 0
	v_add_f32_e32 v81, 1.0, v81
	v_rcp_f32_e32 v82, v81
	v_pk_mul_f32 v[72:73], v[72:73], v[80:81] op_sel_hi:[1,0]
	v_mul_f32_e32 v81, 0xbfb8aa3b, v77
	v_exp_f32_e32 v81, v81
	s_nop 0
	v_add_f32_e32 v81, 1.0, v81
	v_rcp_f32_e32 v83, v81
	v_pk_mul_f32 v[74:75], v[74:75], v[80:81] op_sel_hi:[1,0]
	v_pk_mul_f32 v[68:69], v[68:69], v[80:81] op_sel_hi:[1,0]
	v_pk_mul_f32 v[64:65], v[64:65], v[80:81] op_sel_hi:[1,0]
	v_pk_mul_f32 v[76:77], v[76:77], v[82:83]
	v_pk_mul_f32 v[66:67], v[66:67], v[80:81] op_sel_hi:[1,0]
	v_pk_mul_f32 v[72:73], v[72:73], v[76:77]
	v_pk_mul_f32 v[76:77], v[78:79], v[80:81] op_sel_hi:[1,0]
	s_nop 0
	v_mul_f32_e32 v78, 0xbfb8aa3b, v76
	v_mul_f32_e32 v79, 0xbfb8aa3b, v77
	v_exp_f32_e32 v78, v78
	v_exp_f32_e32 v79, v79
	v_add_f32_e32 v78, 1.0, v78
	v_add_f32_e32 v79, 1.0, v79
	v_rcp_f32_e32 v78, v78
	v_rcp_f32_e32 v79, v79
	s_nop 0
	v_pk_mul_f32 v[76:77], v[76:77], v[78:79]
	s_nop 0
	v_pk_mul_f32 v[74:75], v[74:75], v[76:77]
	v_mul_f32_e32 v76, 0xbfb8aa3b, v68
	v_mul_f32_e32 v77, 0xbfb8aa3b, v69
	v_exp_f32_e32 v76, v76
	v_exp_f32_e32 v77, v77
	v_add_f32_e32 v76, 1.0, v76
	v_add_f32_e32 v77, 1.0, v77
	v_rcp_f32_e32 v76, v76
	v_rcp_f32_e32 v77, v77
	s_nop 0
	v_pk_mul_f32 v[68:69], v[68:69], v[76:77]
	s_nop 0
	v_pk_mul_f32 v[68:69], v[64:65], v[68:69]
	v_pk_mul_f32 v[64:65], v[70:71], v[80:81] op_sel_hi:[1,0]
	s_nop 0
	v_mul_f32_e32 v70, 0xbfb8aa3b, v64
	v_mul_f32_e32 v71, 0xbfb8aa3b, v65
	v_exp_f32_e32 v70, v70
	v_exp_f32_e32 v71, v71
	v_add_f32_e32 v70, 1.0, v70
	v_add_f32_e32 v71, 1.0, v71
	v_rcp_f32_e32 v70, v70
	v_rcp_f32_e32 v71, v71
	s_nop 0
	v_pk_mul_f32 v[64:65], v[64:65], v[70:71]
	s_nop 0
	v_pk_mul_f32 v[70:71], v[66:67], v[64:65]
	v_cvt_pk_bf16_f32 v66, v68, v69
; #define PG8_GAS __attribute__((address_space(1)))
; __device__ __forceinline__ float e_silu(float x) { return x * __builtin_amdgcn_rcpf(1.f + e_exp(-x)); }
; __device__ __forceinline__ unsigned e_pk2(float lo, float hi) { typedef float f2 __attribute__((ext_vector_type(2))); typedef __bf16 b2 __attribute__((ext_vector_type(2))); f2 v = {lo, hi}; b2 b = __builtin_convertvector(v, b2); return __builtin_bit_cast(unsigned, b); }
;     __device__ __forceinline__ void operator()(const f32x4 (&acc)[2][2][4][2], const Unit& u, int wr, int wc, int fr, int fq) const {
;     ...
;                 const int row = row0 + ai * HALF + m * 16;
;                 const float rs = __builtin_amdgcn_rsqf((float)rq[ai][m] * (1.0f / (2048.0f * 16777216.0f)) + 1e-6f);
;                 float o[8];
; #pragma unroll
;                 for (int n = 0; n < 2; ++n)
; #pragma unroll
;                     for (int j = 0; j < 4; ++j) { const float g = acc[ai][0][m][n][j] * rs, up = acc[ai][1][m][n][j] * rs; o[4 * n + j] = e_silu(g) * up; }
;                 u32x4 w; w.x = e_pk2(o[0], o[1]); w.y = e_pk2(o[2], o[3]); w.z = e_pk2(o[4], o[5]); w.w = e_pk2(o[6], o[7]);
;                 *(PG8_GAS u32x4*)(ACT + (size_t)row * ldc + col0) = w;
	v_mad_i64_i32 v[68:69], s[54:55], v166, s92, v[122:123]
	v_cvt_pk_bf16_f32 v64, v72, v73
	v_cvt_pk_bf16_f32 v65, v74, v75
	v_cvt_pk_bf16_f32 v67, v70, v71
	v_lshl_add_u64 v[68:69], v[68:69], 0, v[124:125]
	global_store_dwordx4 v[68:69], v[64:67], off
	s_nop 1
	v_ffbh_u32_e32 v64, v149
	v_min_u32_e32 v66, 32, v64
	v_lshlrev_b64 v[64:65], v66, v[148:149]
	v_min_u32_e32 v64, 1, v64
	v_or_b32_e32 v64, v65, v64
	v_cvt_f32_u32_e32 v64, v64
	v_sub_u32_e32 v65, 32, v66
	v_ldexp_f32 v64, v64, v65
	v_fmamk_f32 v64, v64, 0x2e000000, v226
	v_rsq_f32_e32 v64, v64
	s_nop 0
	v_pk_mul_f32 v[60:61], v[60:61], v[64:65] op_sel_hi:[1,0]
	s_nop 0
	v_mul_f32_e32 v65, 0xbfb8aa3b, v60
	v_exp_f32_e32 v65, v65
	s_nop 0
	v_add_f32_e32 v65, 1.0, v65
	v_rcp_f32_e32 v66, v65
	v_pk_mul_f32 v[56:57], v[56:57], v[64:65] op_sel_hi:[1,0]
	v_mul_f32_e32 v65, 0xbfb8aa3b, v61
	v_exp_f32_e32 v65, v65
	s_nop 0
	v_add_f32_e32 v65, 1.0, v65
	v_rcp_f32_e32 v67, v65
	v_pk_mul_f32 v[58:59], v[58:59], v[64:65] op_sel_hi:[1,0]
	v_pk_mul_f32 v[52:53], v[52:53], v[64:65] op_sel_hi:[1,0]
	v_pk_mul_f32 v[48:49], v[48:49], v[64:65] op_sel_hi:[1,0]
	v_pk_mul_f32 v[60:61], v[60:61], v[66:67]
	v_pk_mul_f32 v[50:51], v[50:51], v[64:65] op_sel_hi:[1,0]
	v_pk_mul_f32 v[56:57], v[56:57], v[60:61]
	v_pk_mul_f32 v[60:61], v[62:63], v[64:65] op_sel_hi:[1,0]
	s_nop 0
	v_mul_f32_e32 v62, 0xbfb8aa3b, v60
	v_mul_f32_e32 v63, 0xbfb8aa3b, v61
	v_exp_f32_e32 v62, v62
	v_exp_f32_e32 v63, v63
	v_add_f32_e32 v62, 1.0, v62
	v_add_f32_e32 v63, 1.0, v63
	v_rcp_f32_e32 v62, v62
	v_rcp_f32_e32 v63, v63
	s_nop 0
	v_pk_mul_f32 v[60:61], v[60:61], v[62:63]
	s_nop 0
	v_pk_mul_f32 v[58:59], v[58:59], v[60:61]
	v_mul_f32_e32 v60, 0xbfb8aa3b, v52
	v_mul_f32_e32 v61, 0xbfb8aa3b, v53
	v_exp_f32_e32 v60, v60
	v_exp_f32_e32 v61, v61
	v_add_f32_e32 v60, 1.0, v60
	v_add_f32_e32 v61, 1.0, v61
	v_rcp_f32_e32 v60, v60
	v_rcp_f32_e32 v61, v61
	s_nop 0
	v_pk_mul_f32 v[52:53], v[52:53], v[60:61]
	s_nop 0
	v_pk_mul_f32 v[52:53], v[48:49], v[52:53]
	v_pk_mul_f32 v[48:49], v[54:55], v[64:65] op_sel_hi:[1,0]
	s_nop 0
	v_mul_f32_e32 v54, 0xbfb8aa3b, v48
	v_mul_f32_e32 v55, 0xbfb8aa3b, v49
	v_exp_f32_e32 v54, v54
	v_exp_f32_e32 v55, v55
	v_add_f32_e32 v54, 1.0, v54
	v_add_f32_e32 v55, 1.0, v55
	v_rcp_f32_e32 v54, v54
	v_rcp_f32_e32 v55, v55
	s_nop 0
	v_pk_mul_f32 v[48:49], v[48:49], v[54:55]
	s_nop 0
	v_pk_mul_f32 v[54:55], v[50:51], v[48:49]
	v_cvt_pk_bf16_f32 v50, v52, v53
	v_mad_i64_i32 v[52:53], s[54:55], v165, s92, v[122:123]
	v_cvt_pk_bf16_f32 v48, v56, v57
	v_cvt_pk_bf16_f32 v49, v58, v59
	v_cvt_pk_bf16_f32 v51, v54, v55
	v_lshl_add_u64 v[52:53], v[52:53], 0, v[124:125]
	global_store_dwordx4 v[52:53], v[48:51], off
	s_nop 1
	v_ffbh_u32_e32 v48, v147
	v_min_u32_e32 v50, 32, v48
	v_lshlrev_b64 v[48:49], v50, v[146:147]
	v_min_u32_e32 v48, 1, v48
	v_or_b32_e32 v48, v49, v48
	v_cvt_f32_u32_e32 v48, v48
	v_sub_u32_e32 v49, 32, v50
	v_ldexp_f32 v48, v48, v49
	v_fmamk_f32 v48, v48, 0x2e000000, v226
	v_rsq_f32_e32 v48, v48
	s_nop 0
	v_pk_mul_f32 v[44:45], v[44:45], v[48:49] op_sel_hi:[1,0]
	s_nop 0
	v_mul_f32_e32 v49, 0xbfb8aa3b, v44
	v_exp_f32_e32 v49, v49
	s_nop 0
	v_add_f32_e32 v49, 1.0, v49
	v_rcp_f32_e32 v50, v49
	v_pk_mul_f32 v[40:41], v[40:41], v[48:49] op_sel_hi:[1,0]
	v_mul_f32_e32 v49, 0xbfb8aa3b, v45
	v_exp_f32_e32 v49, v49
	s_nop 0
	v_add_f32_e32 v49, 1.0, v49
	v_rcp_f32_e32 v51, v49
	v_pk_mul_f32 v[42:43], v[42:43], v[48:49] op_sel_hi:[1,0]
	v_pk_mul_f32 v[36:37], v[36:37], v[48:49] op_sel_hi:[1,0]
	v_pk_mul_f32 v[32:33], v[32:33], v[48:49] op_sel_hi:[1,0]
	v_pk_mul_f32 v[44:45], v[44:45], v[50:51]
	v_pk_mul_f32 v[34:35], v[34:35], v[48:49] op_sel_hi:[1,0]
	v_pk_mul_f32 v[40:41], v[40:41], v[44:45]
	v_pk_mul_f32 v[44:45], v[46:47], v[48:49] op_sel_hi:[1,0]
	s_nop 0
	v_mul_f32_e32 v46, 0xbfb8aa3b, v44
	v_mul_f32_e32 v47, 0xbfb8aa3b, v45
	v_exp_f32_e32 v46, v46
	v_exp_f32_e32 v47, v47
	v_add_f32_e32 v46, 1.0, v46
	v_add_f32_e32 v47, 1.0, v47
	v_rcp_f32_e32 v46, v46
	v_rcp_f32_e32 v47, v47
	s_nop 0
	v_pk_mul_f32 v[44:45], v[44:45], v[46:47]
	s_nop 0
	v_pk_mul_f32 v[42:43], v[42:43], v[44:45]
	v_mul_f32_e32 v44, 0xbfb8aa3b, v36
	v_mul_f32_e32 v45, 0xbfb8aa3b, v37
	v_exp_f32_e32 v44, v44
	v_exp_f32_e32 v45, v45
	v_add_f32_e32 v44, 1.0, v44
	v_add_f32_e32 v45, 1.0, v45
	v_rcp_f32_e32 v44, v44
	v_rcp_f32_e32 v45, v45
	s_nop 0
	v_pk_mul_f32 v[36:37], v[36:37], v[44:45]
	s_nop 0
	v_pk_mul_f32 v[36:37], v[32:33], v[36:37]
	v_pk_mul_f32 v[32:33], v[38:39], v[48:49] op_sel_hi:[1,0]
	s_nop 0
	v_mul_f32_e32 v38, 0xbfb8aa3b, v32
	v_mul_f32_e32 v39, 0xbfb8aa3b, v33
	v_exp_f32_e32 v38, v38
	v_exp_f32_e32 v39, v39
	v_add_f32_e32 v38, 1.0, v38
	v_add_f32_e32 v39, 1.0, v39
	v_rcp_f32_e32 v38, v38
	v_rcp_f32_e32 v39, v39
	s_nop 0
	v_pk_mul_f32 v[32:33], v[32:33], v[38:39]
	s_nop 0
	v_pk_mul_f32 v[38:39], v[34:35], v[32:33]
	v_cvt_pk_bf16_f32 v34, v36, v37
	v_mad_i64_i32 v[36:37], s[54:55], v164, s92, v[122:123]
	v_cvt_pk_bf16_f32 v32, v40, v41
	v_cvt_pk_bf16_f32 v33, v42, v43
	v_cvt_pk_bf16_f32 v35, v38, v39
; #define PG8_GAS __attribute__((address_space(1)))
; __device__ __forceinline__ float e_silu(float x) { return x * __builtin_amdgcn_rcpf(1.f + e_exp(-x)); }
; __device__ __forceinline__ unsigned e_pk2(float lo, float hi) { typedef float f2 __attribute__((ext_vector_type(2))); typedef __bf16 b2 __attribute__((ext_vector_type(2))); f2 v = {lo, hi}; b2 b = __builtin_convertvector(v, b2); return __builtin_bit_cast(unsigned, b); }
;     __device__ __forceinline__ void operator()(const f32x4 (&acc)[2][2][4][2], const Unit& u, int wr, int wc, int fr, int fq) const {
;     ...
;                 const int row = row0 + ai * HALF + m * 16;
;                 const float rs = __builtin_amdgcn_rsqf((float)rq[ai][m] * (1.0f / (2048.0f * 16777216.0f)) + 1e-6f);
;                 float o[8];
; #pragma unroll
;                 for (int n = 0; n < 2; ++n)
; #pragma unroll
;                     for (int j = 0; j < 4; ++j) { const float g = acc[ai][0][m][n][j] * rs, up = acc[ai][1][m][n][j] * rs; o[4 * n + j] = e_silu(g) * up; }
;                 u32x4 w; w.x = e_pk2(o[0], o[1]); w.y = e_pk2(o[2], o[3]); w.z = e_pk2(o[4], o[5]); w.w = e_pk2(o[6], o[7]);
;                 *(PG8_GAS u32x4*)(ACT + (size_t)row * ldc + col0) = w;
	v_lshl_add_u64 v[36:37], v[36:37], 0, v[124:125]
	global_store_dwordx4 v[36:37], v[32:35], off
	s_nop 1
	v_ffbh_u32_e32 v32, v145
	v_min_u32_e32 v34, 32, v32
	v_lshlrev_b64 v[32:33], v34, v[144:145]
	v_min_u32_e32 v32, 1, v32
	v_or_b32_e32 v32, v33, v32
	v_cvt_f32_u32_e32 v32, v32
	v_sub_u32_e32 v33, 32, v34
	v_ldexp_f32 v32, v32, v33
	v_fmamk_f32 v32, v32, 0x2e000000, v226
	v_rsq_f32_e32 v32, v32
	s_nop 0
	v_pk_mul_f32 v[28:29], v[28:29], v[32:33] op_sel_hi:[1,0]
	s_nop 0
	v_mul_f32_e32 v33, 0xbfb8aa3b, v28
	v_exp_f32_e32 v33, v33
	s_nop 0
	v_add_f32_e32 v33, 1.0, v33
	v_rcp_f32_e32 v34, v33
	v_pk_mul_f32 v[24:25], v[24:25], v[32:33] op_sel_hi:[1,0]
	v_mul_f32_e32 v33, 0xbfb8aa3b, v29
	v_exp_f32_e32 v33, v33
	s_nop 0
	v_add_f32_e32 v33, 1.0, v33
	v_rcp_f32_e32 v35, v33
	v_pk_mul_f32 v[26:27], v[26:27], v[32:33] op_sel_hi:[1,0]
	v_pk_mul_f32 v[20:21], v[20:21], v[32:33] op_sel_hi:[1,0]
	v_pk_mul_f32 v[16:17], v[16:17], v[32:33] op_sel_hi:[1,0]
	v_pk_mul_f32 v[28:29], v[28:29], v[34:35]
	v_pk_mul_f32 v[18:19], v[18:19], v[32:33] op_sel_hi:[1,0]
	v_pk_mul_f32 v[24:25], v[24:25], v[28:29]
	v_pk_mul_f32 v[28:29], v[30:31], v[32:33] op_sel_hi:[1,0]
	s_nop 0
	v_mul_f32_e32 v30, 0xbfb8aa3b, v28
	v_mul_f32_e32 v31, 0xbfb8aa3b, v29
	v_exp_f32_e32 v30, v30
	v_exp_f32_e32 v31, v31
	v_add_f32_e32 v30, 1.0, v30
	v_add_f32_e32 v31, 1.0, v31
	v_rcp_f32_e32 v30, v30
	v_rcp_f32_e32 v31, v31
	s_nop 0
	v_pk_mul_f32 v[28:29], v[28:29], v[30:31]
	s_nop 0
	v_pk_mul_f32 v[26:27], v[26:27], v[28:29]
	v_mul_f32_e32 v28, 0xbfb8aa3b, v20
	v_mul_f32_e32 v29, 0xbfb8aa3b, v21
	v_exp_f32_e32 v28, v28
	v_exp_f32_e32 v29, v29
	v_add_f32_e32 v28, 1.0, v28
	v_add_f32_e32 v29, 1.0, v29
	v_rcp_f32_e32 v28, v28
	v_rcp_f32_e32 v29, v29
	s_nop 0
	v_pk_mul_f32 v[20:21], v[20:21], v[28:29]
	s_nop 0
	v_pk_mul_f32 v[20:21], v[16:17], v[20:21]
	v_pk_mul_f32 v[16:17], v[22:23], v[32:33] op_sel_hi:[1,0]
	s_nop 0
	v_mul_f32_e32 v22, 0xbfb8aa3b, v16
	v_mul_f32_e32 v23, 0xbfb8aa3b, v17
	v_exp_f32_e32 v22, v22
	v_exp_f32_e32 v23, v23
	v_add_f32_e32 v22, 1.0, v22
	v_add_f32_e32 v23, 1.0, v23
	v_rcp_f32_e32 v22, v22
	v_rcp_f32_e32 v23, v23
	s_nop 0
	v_pk_mul_f32 v[16:17], v[16:17], v[22:23]
	s_nop 0
	v_pk_mul_f32 v[22:23], v[18:19], v[16:17]
	v_cvt_pk_bf16_f32 v18, v20, v21
	v_mad_i64_i32 v[20:21], s[54:55], v163, s92, v[122:123]
	v_cvt_pk_bf16_f32 v16, v24, v25
	v_cvt_pk_bf16_f32 v17, v26, v27
	v_cvt_pk_bf16_f32 v19, v22, v23
	v_lshl_add_u64 v[20:21], v[20:21], 0, v[124:125]
	global_store_dwordx4 v[20:21], v[16:19], off
	s_nop 1
	v_ffbh_u32_e32 v16, v143
	v_min_u32_e32 v18, 32, v16
	v_lshlrev_b64 v[16:17], v18, v[142:143]
	v_min_u32_e32 v16, 1, v16
	v_or_b32_e32 v16, v17, v16
	v_cvt_f32_u32_e32 v16, v16
	v_sub_u32_e32 v17, 32, v18
	v_ldexp_f32 v16, v16, v17
	v_fmamk_f32 v16, v16, 0x2e000000, v226
	v_rsq_f32_e32 v16, v16
	s_nop 0
	v_pk_mul_f32 v[12:13], v[12:13], v[16:17] op_sel_hi:[1,0]
	s_nop 0
	v_mul_f32_e32 v17, 0xbfb8aa3b, v12
	v_exp_f32_e32 v17, v17
	s_nop 0
	v_add_f32_e32 v17, 1.0, v17
	v_rcp_f32_e32 v18, v17
	v_pk_mul_f32 v[8:9], v[8:9], v[16:17] op_sel_hi:[1,0]
	v_mul_f32_e32 v17, 0xbfb8aa3b, v13
	v_exp_f32_e32 v17, v17
	s_nop 0
	v_add_f32_e32 v17, 1.0, v17
	v_rcp_f32_e32 v19, v17
	v_pk_mul_f32 v[10:11], v[10:11], v[16:17] op_sel_hi:[1,0]
	v_pk_mul_f32 v[4:5], v[4:5], v[16:17] op_sel_hi:[1,0]
	v_pk_mul_f32 v[0:1], v[0:1], v[16:17] op_sel_hi:[1,0]
	v_pk_mul_f32 v[12:13], v[12:13], v[18:19]
	v_pk_mul_f32 v[2:3], v[2:3], v[16:17] op_sel_hi:[1,0]
	v_pk_mul_f32 v[8:9], v[8:9], v[12:13]
	v_pk_mul_f32 v[12:13], v[14:15], v[16:17] op_sel_hi:[1,0]
	s_nop 0
	v_mul_f32_e32 v14, 0xbfb8aa3b, v12
	v_mul_f32_e32 v15, 0xbfb8aa3b, v13
	v_exp_f32_e32 v14, v14
	v_exp_f32_e32 v15, v15
	v_add_f32_e32 v14, 1.0, v14
	v_add_f32_e32 v15, 1.0, v15
	v_rcp_f32_e32 v14, v14
	v_rcp_f32_e32 v15, v15
	s_nop 0
	v_pk_mul_f32 v[12:13], v[12:13], v[14:15]
	s_nop 0
	v_pk_mul_f32 v[10:11], v[10:11], v[12:13]
	v_mul_f32_e32 v12, 0xbfb8aa3b, v4
	v_mul_f32_e32 v13, 0xbfb8aa3b, v5
	v_exp_f32_e32 v12, v12
	v_exp_f32_e32 v13, v13
	v_add_f32_e32 v12, 1.0, v12
	v_add_f32_e32 v13, 1.0, v13
	v_rcp_f32_e32 v12, v12
	v_rcp_f32_e32 v13, v13
	s_nop 0
	v_pk_mul_f32 v[4:5], v[4:5], v[12:13]
	s_nop 0
	v_pk_mul_f32 v[4:5], v[0:1], v[4:5]
	v_pk_mul_f32 v[0:1], v[6:7], v[16:17] op_sel_hi:[1,0]
	s_nop 0
	v_mul_f32_e32 v6, 0xbfb8aa3b, v0
	v_mul_f32_e32 v7, 0xbfb8aa3b, v1
	v_exp_f32_e32 v6, v6
	v_exp_f32_e32 v7, v7
	v_add_f32_e32 v6, 1.0, v6
	v_add_f32_e32 v7, 1.0, v7
	v_rcp_f32_e32 v6, v6
	v_rcp_f32_e32 v7, v7
	s_nop 0
	v_pk_mul_f32 v[0:1], v[0:1], v[6:7]
	s_nop 0
	v_pk_mul_f32 v[6:7], v[2:3], v[0:1]
	v_cvt_pk_bf16_f32 v2, v4, v5
	v_mad_i64_i32 v[4:5], s[54:55], v157, s92, v[122:123]
	v_cvt_pk_bf16_f32 v0, v8, v9
	v_cvt_pk_bf16_f32 v1, v10, v11
	v_cvt_pk_bf16_f32 v3, v6, v7
	v_lshl_add_u64 v[4:5], v[4:5], 0, v[124:125]
	s_mov_b64 s[54:55], -1
	global_store_dwordx4 v[4:5], v[0:3], off
	s_cbranch_vccnz .LBB0_207
	s_andn2_b64 vcc, exec, s[0:1]
	s_cbranch_vccnz .LBB0_206
	s_barrier
	s_branch .LBB0_206

; #define PG8_GAS __attribute__((address_space(1)))
; #define PG8_STAGE(bufoff, gbase, voff) do { _Pragma("unroll") for (int _i = 0; _i < 2; ++_i) \
;         __builtin_amdgcn_global_load_lds((const unsigned*)((const char*)(gbase) + (voff)[_i]), (PG8_LAS unsigned*)(lds + (bufoff) + ldsw + _i * 8192), 16, 0, 0); } while (0)
; #define PG8_WAIT_V(n) asm volatile("s_waitcnt vmcnt(" #n ")" ::: "memory")
; #define PG8_BAR __builtin_amdgcn_s_barrier()
;     __device__ __forceinline__ void operator()(const f32x4 (&acc)[2][2][4][2], const Unit& u, int wr, int wc, int fr, int fq) const {
;         const int row0 = u.pm * BM + wr * 64 + fr, col0 = u.pn * BM + wc * 32 + 8 * fq;
;         const bool tail = (u.pn == 30);
;         unsigned long long rq[2][4];
; #pragma unroll
;         for (int ai = 0; ai < 2; ++ai)
; #pragma unroll
;             for (int m = 0; m < 4; ++m) rq[ai][m] = ((const PG8_GAS unsigned long long*)rowsq)[row0 + ai * HALF + m * 16];
; template <class Epi, class Sched, bool ALIGN_EPI = false, bool SP2 = false>
; __device__ __forceinline__ void gemm_phase(PG8_LAS unsigned char* lds, const Gemm g, const Sched& S, const Epi& E, const int tid) {
;     ...
;         PG8_STAGE(PG8_SB(0, 0), cB, voffB); PG8_STAGE(PG8_SA(0, 0), cA, voffA); PG8_STAGE(PG8_SB(0, 1), cB + hstep, voffB); PG8_STAGE(PG8_SA(0, 1), cA + hstep, voffA);
;         if (wr == 1) PG8_BAR;
;         PG8_WAIT_V(4); PG8_BAR;
;         PG8_STAGE(PG8_SB(1, 0), cB + kstep, voffB); PG8_STAGE(PG8_SA(1, 0), cA + kstep, voffA); PG8_STAGE(PG8_SB(1, 1), cB + hstep + kstep, voffB);
;         PG8_WAIT_V(6); PG8_BAR;
.LBB0_482:
	v_readlane_b32 s30, v255, 17
	s_mul_i32 s44, s30, 0x30000
	s_add_u32 s30, s40, 0x32500000
	s_addc_u32 s31, s41, 0
	s_add_u32 s44, s40, s44
	s_addc_u32 s45, s41, 0
	v_bfe_u32 v16, v14, 4, 2
	s_add_u32 s44, s44, 0x20000
	v_and_b32_e32 v15, 15, v14
	v_lshlrev_b32_e32 v18, 4, v16
	v_lshlrev_b32_e32 v14, 2, v14
	s_addc_u32 s45, s45, 0
	s_and_b32 s50, s48, 3
	v_lshl_or_b32 v101, s47, 6, v15
	v_lshl_or_b32 v15, v15, 6, v18
	s_lshl_b32 s47, s47, 13
	v_and_b32_e32 v14, 32, v14
	s_add_i32 m0, s63, 0x18000
	v_lshl_add_u64 v[6:7], v[6:7], 0, s[28:29]
	v_bitop3_b32 v18, v15, s47, v14 bitop3:0xde
	s_lshl_b32 s47, s50, 12
	s_waitcnt vmcnt(2)
	s_barrier
	global_load_lds_dwordx4 v[6:7], off
	v_lshl_add_u64 v[4:5], v[4:5], 0, s[28:29]
	s_add_i32 m0, s63, 0x1a000
	s_add_i32 s67, s63, 0x8000
	s_add_i32 s68, s63, 0xa000
	global_load_lds_dwordx4 v[4:5], off
	v_lshl_add_u64 v[0:1], v[0:1], 0, s[28:29]
	s_mov_b32 m0, s67
	s_add_u32 s48, s42, 0x80080
	global_load_lds_dwordx4 v[0:1], off
	v_lshl_add_u64 v[0:1], v[2:3], 0, s[28:29]
	s_mov_b32 m0, s68
	s_addc_u32 s49, s43, 0
	global_load_lds_dwordx4 v[0:1], off
	s_add_i32 m0, s63, 0x1c000
	v_lshl_add_u64 v[0:1], s[48:49], 0, v[96:97]
	global_load_lds_dwordx4 v[0:1], off
	v_lshl_add_u64 v[0:1], s[48:49], 0, v[98:99]
	s_add_i32 m0, s63, 0x1e000
	s_cmpk_lt_u32 s46, 0x100
	global_load_lds_dwordx4 v[0:1], off
	v_lshlrev_b32_e32 v0, 5, v16
	v_mov_b32_e32 v1, v97
	v_lshl_add_u64 v[0:1], s[40:41], 0, v[0:1]
	s_mov_b64 s[40:41], 0x39d00000
	v_lshl_add_u64 v[138:139], v[0:1], 0, s[40:41]
	v_lshlrev_b32_e32 v0, 15, v8
	v_and_b32_e32 v0, 0xffff0000, v0
	v_lshl_add_u32 v0, v9, 12, v0
	v_and_b32_e32 v1, 1, v8
	v_lshl_or_b32 v0, v1, 6, v0
	v_lshl_add_u32 v140, v10, 1, v0
	v_lshlrev_b32_e32 v0, 15, v12
	v_and_b32_e32 v0, 0xffff0000, v0
	v_bitop3_b32 v163, v15, s47, v14 bitop3:0xde
	s_waitcnt vmcnt(6)
	s_cselect_b64 s[46:47], -1, 0
	s_cmp_eq_u32 s50, 0
	v_lshl_add_u32 v0, v11, 12, v0
	v_and_b32_e32 v1, 1, v12
	v_lshlrev_b32_e32 v17, 3, v16
	s_cselect_b64 s[48:49], -1, 0
	v_cmp_gt_u32_e32 vcc, 2, v16
	v_lshl_or_b32 v0, v1, 6, v0
	v_readlane_b32 s40, v254, 9
	s_mov_b32 s69, 0
	s_and_b64 s[48:49], s[48:49], vcc
	v_lshl_or_b32 v164, s50, 5, v17
	v_mov_b32_e32 v141, v97
	v_lshl_add_u32 v142, v13, 1, v0
	v_mov_b32_e32 v143, v97
	v_add_u32_e32 v165, 0, v18
	v_readlane_b32 s70, v253, 58
	s_mov_b32 s71, s40
	v_lshl_add_u32 v233, s71, 8, v101
	v_lshlrev_b32_e32 v233, 3, v233
	global_load_dwordx2 v[234:235], v233, s[44:45]
	global_load_dwordx2 v[236:237], v233, s[44:45] offset:128
	global_load_dwordx2 v[238:239], v233, s[44:45] offset:256
	global_load_dwordx2 v[240:241], v233, s[44:45] offset:384
	global_load_dwordx2 v[242:243], v233, s[44:45] offset:1024
	global_load_dwordx2 v[246:247], v233, s[44:45] offset:1152
	global_load_dwordx2 v[248:249], v233, s[44:45] offset:1280
	global_load_dwordx2 v[250:251], v233, s[44:45] offset:1408
	s_barrier
	v_readlane_b32 s41, v254, 10
	s_branch .LBB0_485

; #define PG8_GAS __attribute__((address_space(1)))
; __device__ __forceinline__ unsigned e_pk2(float lo, float hi) { typedef float f2 __attribute__((ext_vector_type(2))); typedef __bf16 b2 __attribute__((ext_vector_type(2))); f2 v = {lo, hi}; b2 b = __builtin_convertvector(v, b2); return __builtin_bit_cast(unsigned, b); }
;     __device__ __forceinline__ void operator()(const f32x4 (&acc)[2][2][4][2], const Unit& u, int wr, int wc, int fr, int fq) const {
;     ...
;             for (int m = 0; m < 4; ++m) rq[ai][m] = ((const PG8_GAS unsigned long long*)rowsq)[row0 + ai * HALF + m * 16];
; #pragma unroll
;         for (int ai = 0; ai < 2; ++ai)
; #pragma unroll
;             for (int m = 0; m < 4; ++m) {
;                 const int row = row0 + ai * HALF + m * 16;
;                 const float rs = __builtin_amdgcn_rsqf((float)rq[ai][m] * (1.0f / (2048.0f * 16777216.0f)) + 1e-6f);
;                 if (!tail) {
; #pragma unroll
;                     for (int bj = 0; bj < 2; ++bj) {
;                         const f32x4 v0 = acc[ai][bj][m][0] * rs, v1 = acc[ai][bj][m][1] * rs;
;                         u32x4 w; w.x = e_pk2(v0[0], v0[1]); w.y = e_pk2(v0[2], v0[3]); w.z = e_pk2(v1[0], v1[1]); w.w = e_pk2(v1[2], v1[3]);
;                         *(PG8_GAS u32x4*)(P + (size_t)row * ldp + col0 + bj * HALF) = w;
;                     }
.LBB0_491:
	v_lshl_add_u32 v146, s71, 8, v101
	v_ashrrev_i32_e32 v147, 31, v146
	v_mov_b64_e32 v[166:167], v[234:235]
	v_mov_b64_e32 v[160:161], v[236:237]
	v_mov_b64_e32 v[158:159], v[238:239]
	v_mov_b64_e32 v[156:157], v[240:241]
	v_mov_b64_e32 v[154:155], v[242:243]
	v_mov_b64_e32 v[152:153], v[246:247]
	v_mov_b64_e32 v[150:151], v[248:249]
	v_mov_b64_e32 v[148:149], v[250:251]
	s_and_b32 s100, s52, 31
	v_lshl_add_u32 v233, s100, 8, v101
	v_lshlrev_b32_e32 v233, 3, v233
	global_load_dwordx2 v[234:235], v233, s[44:45]
	global_load_dwordx2 v[236:237], v233, s[44:45] offset:128
	global_load_dwordx2 v[238:239], v233, s[44:45] offset:256
	global_load_dwordx2 v[240:241], v233, s[44:45] offset:384
	global_load_dwordx2 v[242:243], v233, s[44:45] offset:1024
	global_load_dwordx2 v[246:247], v233, s[44:45] offset:1152
	global_load_dwordx2 v[248:249], v233, s[44:45] offset:1280
	global_load_dwordx2 v[250:251], v233, s[44:45] offset:1408
	v_lshl_or_b32 v144, s70, 8, v164
	s_cmp_lg_u32 s70, 30
	s_cselect_b64 s[58:59], -1, 0
	s_cmp_eq_u32 s70, 30
	s_mov_b64 s[42:43], -1
	v_ffbh_u32_e32 v145, v167
	v_min_u32_e32 v145, 32, v145
	v_lshlrev_b64 v[166:167], v145, v[166:167]
	v_min_u32_e32 v162, 1, v166
	v_or_b32_e32 v162, v167, v162
	v_cvt_f32_u32_e32 v162, v162
	v_sub_u32_e32 v145, 32, v145
	v_ldexp_f32 v145, v162, v145
	v_fmamk_f32 v145, v145, 0x2e000000, v226
	v_rsq_f32_e32 v162, v145
	v_ashrrev_i32_e32 v145, 31, v144
	s_cbranch_scc1 .LBB0_493
	v_pk_mul_f32 v[168:169], v[124:125], v[162:163] op_sel_hi:[1,0]
	v_pk_mul_f32 v[166:167], v[122:123], v[162:163] op_sel_hi:[1,0]
	v_pk_mul_f32 v[170:171], v[120:121], v[162:163] op_sel_hi:[1,0]
	v_cvt_pk_bf16_f32 v166, v166, v167
	v_cvt_pk_bf16_f32 v167, v168, v169
	v_cvt_pk_bf16_f32 v169, v170, v171
	v_mov_b64_e32 v[170:171], s[30:31]
	v_pk_mul_f32 v[172:173], v[118:119], v[162:163] op_sel_hi:[1,0]
	v_mad_i64_i32 v[170:171], s[42:43], v146, s97, v[170:171]
	v_cvt_pk_bf16_f32 v168, v172, v173
	v_lshl_add_u64 v[170:171], v[144:145], 1, v[170:171]
	global_store_dwordx4 v[170:171], v[166:169], off
	v_pk_mul_f32 v[132:133], v[132:133], v[162:163] op_sel_hi:[1,0]
	v_pk_mul_f32 v[130:131], v[130:131], v[162:163] op_sel_hi:[1,0]
	v_pk_mul_f32 v[166:167], v[128:129], v[162:163] op_sel_hi:[1,0]
	v_pk_mul_f32 v[128:129], v[126:127], v[162:163] op_sel_hi:[1,0]
	v_cvt_pk_bf16_f32 v126, v130, v131
	v_cvt_pk_bf16_f32 v127, v132, v133
	v_cvt_pk_bf16_f32 v128, v128, v129
	v_cvt_pk_bf16_f32 v129, v166, v167
	s_mov_b64 s[42:43], 0
	global_store_dwordx4 v[170:171], v[126:129], off offset:256

; __global__ void __launch_bounds__(512, 2) mega_fwd(Args args) {
	.amdhsa_kernel _Z8mega_fwd4Args
		.amdhsa_group_segment_fixed_size 0
		.amdhsa_private_segment_fixed_size 0
		.amdhsa_kernarg_size 472
		.amdhsa_user_sgpr_count 2
		.amdhsa_user_sgpr_dispatch_ptr 0
		.amdhsa_user_sgpr_queue_ptr 0
		.amdhsa_user_sgpr_kernarg_segment_ptr 1
		.amdhsa_user_sgpr_dispatch_id 0
		.amdhsa_user_sgpr_kernarg_preload_length 0
		.amdhsa_user_sgpr_kernarg_preload_offset 0
		.amdhsa_user_sgpr_private_segment_size 0
		.amdhsa_uses_dynamic_stack 0
		.amdhsa_enable_private_segment 0
		.amdhsa_system_sgpr_workgroup_id_x 1
		.amdhsa_system_sgpr_workgroup_id_y 0
		.amdhsa_system_sgpr_workgroup_id_z 0
		.amdhsa_system_sgpr_workgroup_info 0
		.amdhsa_system_vgpr_workitem_id 0
		.amdhsa_next_free_vgpr 256
		.amdhsa_next_free_sgpr 102
		.amdhsa_accum_offset 256
		.amdhsa_reserve_vcc 1
		.amdhsa_float_round_mode_32 0
		.amdhsa_float_round_mode_16_64 0
		.amdhsa_float_denorm_mode_32 3
		.amdhsa_float_denorm_mode_16_64 3
		.amdhsa_dx10_clamp 1
		.amdhsa_ieee_mode 1
		.amdhsa_fp16_overflow 0
		.amdhsa_tg_split 0
		.amdhsa_exception_fp_ieee_invalid_op 0
		.amdhsa_exception_fp_denorm_src 0
		.amdhsa_exception_fp_ieee_div_zero 0
		.amdhsa_exception_fp_ieee_overflow 0
		.amdhsa_exception_fp_ieee_underflow 0
		.amdhsa_exception_fp_ieee_inexact 0
		.amdhsa_exception_int_div_zero 0
	.end_amdhsa_kernel
